# attention: each wave touches the next query block's new K / V^T / Q lines at the start of compute (L2 prefetch) so the next window staging hits L2; blocked hidden layout; V^T rounds reversed
# baseline (speedup 1.0000x reference)
.LBB0_49:
	s_and_b32 s50, s45, 31
	s_ashr_i32 vcc_lo, s45, 9
	s_lshl_b32 s48, s50, 8
	s_ashr_i32 vcc_hi, vcc_lo, 31
	v_readlane_b32 s46, v254, 55
	s_addk_i32 s48, 0xff00
	s_lshl_b64 s[52:53], vcc, 24
	s_mov_b32 m0, s46
	s_add_u32 s46, s90, s52
	s_addc_u32 s68, s91, s53
	s_lshl_b32 s49, s45, 1
	s_and_b32 s49, s49, 0x3c0
	s_lshl_b32 s96, s49, 1
	v_add_u32_e32 v0, s48, v125
	s_add_u32 s98, s46, s96
	v_max_i32_e32 v0, 0, v0
	v_mov_b32_e32 v1, v49
	s_addc_u32 s99, s68, 0
	v_lshlrev_b64 v[0:1], 11, v[0:1]
	v_lshl_add_u64 v[0:1], s[98:99], 0, v[0:1]
	v_lshl_add_u64 v[0:1], v[0:1], 0, v[100:101]
	s_barrier
	global_load_lds_dwordx4 v[0:1], off
	v_add_u32_e32 v0, s48, v126
	v_max_i32_e32 v0, 0, v0
	v_mov_b32_e32 v1, v49
	v_lshlrev_b64 v[0:1], 11, v[0:1]
	v_lshl_add_u64 v[0:1], s[98:99], 0, v[0:1]
	v_readlane_b32 s46, v254, 56
	v_lshl_add_u64 v[0:1], v[0:1], 0, v[102:103]
	s_mov_b32 m0, s46
	v_readlane_b32 s46, v254, 57
	global_load_lds_dwordx4 v[0:1], off
	v_add_u32_e32 v0, s48, v127
	v_max_i32_e32 v0, 0, v0
	v_mov_b32_e32 v1, v49
	v_lshlrev_b64 v[0:1], 11, v[0:1]
	v_lshl_add_u64 v[0:1], s[98:99], 0, v[0:1]
	v_lshl_add_u64 v[0:1], v[0:1], 0, v[104:105]
	s_mov_b32 m0, s46
	v_readlane_b32 s46, v254, 58
	global_load_lds_dwordx4 v[0:1], off
	v_add_u32_e32 v0, s48, v128
	v_max_i32_e32 v0, 0, v0
	v_mov_b32_e32 v1, v49
	v_lshlrev_b64 v[0:1], 11, v[0:1]
	v_lshl_add_u64 v[0:1], s[98:99], 0, v[0:1]
	v_lshl_add_u64 v[0:1], v[0:1], 0, v[106:107]
	s_mov_b32 m0, s46
	v_readlane_b32 s46, v254, 59
	global_load_lds_dwordx4 v[0:1], off
	v_add_u32_e32 v0, s48, v129
	v_max_i32_e32 v0, 0, v0
	v_mov_b32_e32 v1, v49
	v_lshlrev_b64 v[0:1], 11, v[0:1]
	v_lshl_add_u64 v[0:1], s[98:99], 0, v[0:1]
	v_lshl_add_u64 v[0:1], v[0:1], 0, v[108:109]
	s_mov_b32 m0, s46
	v_readlane_b32 s46, v254, 60
	global_load_lds_dwordx4 v[0:1], off
	v_add_u32_e32 v0, s48, v130
	v_max_i32_e32 v0, 0, v0
	v_mov_b32_e32 v1, v49
	v_lshlrev_b64 v[0:1], 11, v[0:1]
	v_lshl_add_u64 v[0:1], s[98:99], 0, v[0:1]
	v_lshl_add_u64 v[0:1], v[0:1], 0, v[110:111]
	s_mov_b32 m0, s46
	s_mov_b32 s97, s51
	global_load_lds_dwordx4 v[0:1], off
	v_add_u32_e32 v0, s48, v131
	v_max_i32_e32 v0, 0, v0
	v_mov_b32_e32 v1, v49
	v_lshlrev_b64 v[0:1], 11, v[0:1]
	v_lshl_add_u64 v[0:1], s[98:99], 0, v[0:1]
	v_lshl_add_u64 v[0:1], v[0:1], 0, v[112:113]
	s_mov_b32 m0, s75
	s_nop 0
	global_load_lds_dwordx4 v[0:1], off
	v_add_u32_e32 v0, s48, v132
	v_max_i32_e32 v0, 0, v0
	v_mov_b32_e32 v1, v49
	v_lshlrev_b64 v[0:1], 11, v[0:1]
	v_lshl_add_u64 v[0:1], s[98:99], 0, v[0:1]
	s_lshl_b64 s[98:99], vcc, 14
	s_add_u32 s46, s92, s98
	s_addc_u32 s68, s93, s99
	s_add_i32 s98, s49, s1
	v_lshl_add_u64 v[0:1], v[0:1], 0, v[114:115]
	s_mov_b32 m0, s76
	s_ashr_i32 s99, s98, 31
	global_load_lds_dwordx4 v[0:1], off
	v_add_u32_e32 v0, s48, v133
	s_lshl_b64 s[98:99], s[98:99], 17
	v_max_i32_e32 v0, 0, v0
	s_add_u32 s98, s46, s98
	s_addc_u32 s99, s68, s99
	v_lshlrev_b32_e32 v0, 1, v0
	s_mov_b32 m0, s77
	s_nop 0
	global_load_lds_dwordx4 v0, s[98:99]
	s_add_i32 s98, s49, s0
	s_ashr_i32 s99, s98, 31
	v_add_u32_e32 v0, s48, v134
	s_lshl_b64 s[98:99], s[98:99], 17
	v_max_i32_e32 v0, 0, v0
	s_add_u32 s98, s46, s98
	s_addc_u32 s99, s68, s99
	v_lshlrev_b32_e32 v0, 1, v0
	s_mov_b32 m0, s84
	s_nop 0
	global_load_lds_dwordx4 v0, s[98:99]
	s_add_i32 s98, s49, s60
	s_ashr_i32 s99, s98, 31
	v_add_u32_e32 v0, s48, v135
	s_lshl_b64 s[98:99], s[98:99], 17
	v_max_i32_e32 v0, 0, v0
	s_add_u32 s98, s46, s98
	s_addc_u32 s99, s68, s99
	v_lshlrev_b32_e32 v0, 1, v0
	s_mov_b32 m0, s85
	s_nop 0
	global_load_lds_dwordx4 v0, s[98:99]
	s_add_i32 s98, s49, s64
	s_ashr_i32 s99, s98, 31
	v_add_u32_e32 v0, s48, v136
	s_lshl_b64 s[98:99], s[98:99], 17
	v_max_i32_e32 v0, 0, v0
	s_add_u32 s98, s46, s98
	s_addc_u32 s99, s68, s99
	v_lshlrev_b32_e32 v0, 1, v0
	s_mov_b32 m0, s88
	s_nop 0
	global_load_lds_dwordx4 v0, s[98:99]
	s_add_i32 s98, s49, s54
	s_ashr_i32 s99, s98, 31
	v_add_u32_e32 v0, s48, v137
	s_lshl_b64 s[98:99], s[98:99], 17
	v_max_i32_e32 v0, 0, v0
	s_add_u32 s98, s46, s98
	s_addc_u32 s99, s68, s99
	v_lshlrev_b32_e32 v0, 1, v0
	s_mov_b32 m0, s89
	s_nop 0
	global_load_lds_dwordx4 v0, s[98:99]
	s_add_i32 s98, s49, s63
	s_ashr_i32 s99, s98, 31
	v_add_u32_e32 v0, s48, v138
	s_lshl_b64 s[98:99], s[98:99], 17
	v_max_i32_e32 v0, 0, v0
	s_add_u32 s98, s46, s98
	s_addc_u32 s99, s68, s99
	v_lshlrev_b32_e32 v0, 1, v0
	s_mov_b32 m0, s94
	s_nop 0
	global_load_lds_dwordx4 v0, s[98:99]
	s_add_i32 s98, s49, s67
	s_ashr_i32 s99, s98, 31
	v_add_u32_e32 v0, s48, v139
	s_lshl_b64 s[98:99], s[98:99], 17
	v_max_i32_e32 v0, 0, v0
	s_add_u32 s98, s46, s98
	s_addc_u32 s99, s68, s99
	v_lshlrev_b32_e32 v0, 1, v0
	s_mov_b32 m0, s95
	s_nop 0
	global_load_lds_dwordx4 v0, s[98:99]
	s_add_i32 s98, s49, s4
	s_ashr_i32 s99, s98, 31
	v_add_u32_e32 v0, s48, v140
	s_lshl_b64 s[98:99], s[98:99], 17
	v_max_i32_e32 v0, 0, v0
	s_add_u32 s98, s46, s98
	s_addc_u32 s99, s68, s99
	v_lshlrev_b32_e32 v0, 1, v0
	s_mov_b32 m0, s44
	s_lshl_b32 s46, s50, 3
	global_load_lds_dwordx4 v0, s[98:99]
	s_add_i32 s98, s46, s33
	s_ashr_i32 s99, s98, 31
	s_lshl_b64 vcc, vcc, 13
	s_lshl_b64 s[68:69], s[98:99], 5
	s_add_u32 s46, s68, vcc_lo
	s_addc_u32 s50, s69, vcc_hi
	v_mov_b32_e32 v119, s50
	v_or_b32_e32 v118, s46, v94
	v_readlane_b32 s68, v254, 49
	v_lshlrev_b64 v[0:1], 11, v[118:119]
	v_readlane_b32 s69, v254, 50
	s_cmp_lt_i32 s98, 0
	s_nop 0
	v_lshl_add_u64 v[0:1], s[68:69], 0, v[0:1]
	v_lshl_add_u64 v[0:1], v[0:1], 0, s[96:97]
	v_lshl_add_u64 v[0:1], v[0:1], 0, v[48:49]
	global_load_dwordx4 v[50:53], v[0:1], off
	global_load_dwordx4 v[54:57], v[0:1], off offset:32
	global_load_dwordx4 v[58:61], v[0:1], off offset:64
	global_load_dwordx4 v[62:65], v[0:1], off offset:96
	s_waitcnt vmcnt(0)
	s_waitcnt vmcnt(0) lgkmcnt(0)
	s_barrier
	s_cbranch_scc1 .LBB0_47
	s_and_b32 s100, s45, 31
	s_movk_i32 s101, 0x200
	s_cmp_eq_u32 s100, 31
	s_cselect_b32 s101, 0x100, s101
	s_add_i32 s100, vcc_lo, s48
	s_add_i32 s100, s100, s101
	v_add_u32_e32 v248, s100, v237
	v_lshl_add_u32 v248, v248, 11, s96
	v_and_b32_e32 v249, 3, v237
	v_lshl_add_u32 v249, v249, 6, s100
	v_lshlrev_b32_e32 v249, 1, v249
	v_bfe_u32 v250, v237, 2, 6
	v_add_u32_e32 v250, s49, v250
	v_lshl_add_u32 v249, v250, 17, v249
	v_bfe_u32 v250, v237, 8, 1
	v_cmp_eq_u32_e64 s[100:101], 0, v250
	s_nop 1
	v_cndmask_b32_e64 v248, v249, v248, s[100:101]
	s_cmp_lt_u32 s33, 4
	s_cselect_b32 s100, s90, s92
	s_cselect_b32 s101, s91, s93
	s_nop 4
	global_load_dword v250, v248, s[100:101]
	v_readlane_b32 s100, v254, 49
	v_readlane_b32 s101, v254, 50
	s_nop 0
	s_cselect_b32 s100, s100, s92
	s_cselect_b32 s101, s101, s93
	s_nop 4
	global_load_dword v251, v248, s[100:101]
	v_or_b32_e32 v0, s49, v94
	v_lshlrev_b32_e32 v0, 17, v0
	v_mov_b32_e32 v1, v49
	v_lshl_add_u64 v[0:1], s[92:93], 0, v[0:1]
	s_lshl_b32 s50, s98, 5
	v_lshl_add_u64 v[0:1], vcc, 1, v[0:1]
	s_sub_i32 s46, s50, s48
	v_lshl_add_u64 v[120:121], v[0:1], 0, v[48:49]
	s_cmp_gt_i32 s46, -1
	s_mov_b64 s[48:49], -1
	s_cbranch_scc1 .LBB0_52
	v_mov_b32_e32 v1, vcc_hi
	v_or_b32_e32 v0, vcc_lo, v96
	v_lshlrev_b64 v[0:1], 11, v[0:1]
	v_lshl_add_u64 v[0:1], s[90:91], 0, v[0:1]
	s_mov_b32 s97, s51
	v_lshl_add_u64 v[0:1], v[0:1], 0, s[96:97]
	s_mov_b32 s99, s51
	v_lshl_add_u64 v[0:1], v[0:1], 0, v[48:49]
	s_lshl_b64 s[48:49], s[98:99], 16
	v_lshl_add_u64 v[4:5], v[0:1], 0, s[48:49]
	s_lshl_b32 s50, s50, 1
	global_load_dwordx4 v[0:3], v[4:5], off
	global_load_dwordx4 v[26:29], v[4:5], off offset:32
	global_load_dwordx4 v[40:43], v[4:5], off offset:64
	global_load_dwordx4 v[44:47], v[4:5], off offset:96
	v_lshl_add_u64 v[4:5], v[120:121], 0, s[50:51]
	global_load_dwordx4 v[18:21], v[4:5], off
	global_load_dwordx4 v[32:35], v[4:5], off offset:32
	v_add_co_u32_e32 v4, vcc, 0x400000, v4
	s_mov_b64 s[48:49], 0
	s_nop 0
	v_addc_co_u32_e32 v5, vcc, 0, v5, vcc
	global_load_dwordx4 v[22:25], v[4:5], off
	global_load_dwordx4 v[36:39], v[4:5], off offset:32
